# v46 + deleted the 122 redundant canonicalizing v_max x,x,x ahead of max(0,x) in the relu^2 epilogue (bit-identical results)
# speedup vs baseline: 1.0080x; 1.0080x over previous
;     DI void operator()(const f32x4 (&acc)[2][2][4][2], const pg8::Unit& u, int wr, int wc, int fr, int fq) const {
;         const int row0 = u.pm * 256 + wr * 64 + fr, col0 = u.pn * 256 + wc * 32 + 8 * fq;
;         f32x4 pp[8];
; #pragma unroll
;         for (int g = 0; g < 8; ++g) pp[g] = *(const f32x4*)(ssq + (size_t)(row0 + (g >> 2) * 128 + (g & 3) * 16) * 16 + 4 * fq);
; #pragma unroll
;         for (int ai = 0; ai < 2; ++ai)
; #pragma unroll
;             for (int m = 0; m < 4; ++m) {
;                 const int row = row0 + ai * 128 + m * 16;
;                 const f32x4 p = pp[ai * 4 + m];
;                 float s = (p[0] + p[1]) + (p[2] + p[3]);
;                 s += __shfl_xor(s, 16); s += __shfl_xor(s, 32);
;                 const float rstd = rsqrtf(s * (1.0f / D) + EPS);
;                 bf16_t* rowp = O + (size_t)row * ldc + col0;
; #pragma unroll
;                 for (int bj = 0; bj < 2; ++bj) {
;                     f32x4 v0 = acc[ai][bj][m][0] * rstd, v1 = acc[ai][bj][m][1] * rstd;
;                     if (act) {
; #pragma unroll
;                         for (int k = 0; k < 4; ++k) { float a = fmaxf(v0[k], 0.f), b = fmaxf(v1[k], 0.f); v0[k] = a * a; v1[k] = b * b; }
.LBB0_470:
	v_lshl_add_u32 v190, s38, 8, v214
	v_ashrrev_i32_e32 v191, 31, v190
	v_lshlrev_b64 v[56:57], 6, v[190:191]
	v_lshl_add_u64 v[56:57], v[170:171], 0, v[56:57]
	global_load_dwordx4 v[192:195], v[56:57], off
	v_or_b32_e32 v188, 16, v190
	v_ashrrev_i32_e32 v189, 31, v188
	v_lshlrev_b64 v[56:57], 6, v[188:189]
	v_or_b32_e32 v186, 32, v190
	v_lshl_add_u64 v[56:57], v[170:171], 0, v[56:57]
	v_ashrrev_i32_e32 v187, 31, v186
	global_load_dwordx4 v[152:155], v[56:57], off
	v_lshlrev_b64 v[56:57], 6, v[186:187]
	v_or_b32_e32 v184, 48, v190
	v_lshl_add_u64 v[56:57], v[170:171], 0, v[56:57]
	v_ashrrev_i32_e32 v185, 31, v184
	global_load_dwordx4 v[148:151], v[56:57], off
	v_lshlrev_b64 v[56:57], 6, v[184:185]
	v_add_u32_e32 v182, 0x80, v190
	v_lshl_add_u64 v[56:57], v[170:171], 0, v[56:57]
	v_ashrrev_i32_e32 v183, 31, v182
	global_load_dwordx4 v[136:139], v[56:57], off
	v_lshlrev_b64 v[56:57], 6, v[182:183]
	v_add_u32_e32 v180, 0x90, v190
	v_lshl_add_u64 v[56:57], v[170:171], 0, v[56:57]
	v_ashrrev_i32_e32 v181, 31, v180
	global_load_dwordx4 v[116:119], v[56:57], off
	v_lshlrev_b64 v[56:57], 6, v[180:181]
	v_add_u32_e32 v178, 0xa0, v190
	v_lshl_add_u64 v[56:57], v[170:171], 0, v[56:57]
	v_ashrrev_i32_e32 v179, 31, v178
	global_load_dwordx4 v[96:99], v[56:57], off
	v_lshlrev_b64 v[56:57], 6, v[178:179]
	v_add_u32_e32 v176, 0xb0, v190
	v_lshl_add_u64 v[56:57], v[170:171], 0, v[56:57]
	v_ashrrev_i32_e32 v177, 31, v176
	global_load_dwordx4 v[76:79], v[56:57], off
	v_lshlrev_b64 v[56:57], 6, v[176:177]
	v_lshl_add_u64 v[56:57], v[170:171], 0, v[56:57]
	global_load_dwordx4 v[56:59], v[56:57], off
	v_and_b32_e32 v179, 64, v198
	v_xor_b32_e32 v177, 16, v198
	v_add_u32_e32 v179, 64, v179
	v_cmp_lt_i32_e32 vcc, v177, v179
	v_xor_b32_e32 v181, 32, v198
	v_readlane_b32 s48, v250, 18
	v_cndmask_b32_e32 v177, v198, v177, vcc
	v_cmp_lt_i32_e32 vcc, v181, v179
	v_lshlrev_b32_e32 v177, 2, v177
	v_readlane_b32 s49, v250, 19
	v_cndmask_b32_e32 v179, v198, v181, vcc
	v_lshlrev_b32_e32 v179, 2, v179
	v_readlane_b32 s50, v250, 20
	v_readlane_b32 s51, v250, 21
	v_readlane_b32 s52, v250, 22
	v_readlane_b32 s53, v250, 23
	v_readlane_b32 s54, v250, 24
	v_readlane_b32 s55, v250, 25
	v_readlane_b32 s56, v250, 26
	v_readlane_b32 s57, v250, 27
	v_readlane_b32 s58, v250, 28
	v_readlane_b32 s59, v250, 29
	v_readlane_b32 s60, v250, 30
	v_readlane_b32 s61, v250, 31
	v_readlane_b32 s62, v250, 32
	v_readlane_b32 s63, v250, 33
	s_waitcnt vmcnt(0)
	v_add_f32_e32 v220, v193, v192
	v_add_f32_e32 v221, v194, v195
	v_add_f32_e32 v220, v220, v221
	v_add_f32_e32 v222, v153, v152
	v_add_f32_e32 v223, v154, v155
	v_add_f32_e32 v222, v222, v223
	v_add_f32_e32 v224, v149, v148
	v_add_f32_e32 v225, v150, v151
	v_add_f32_e32 v224, v224, v225
	v_add_f32_e32 v226, v137, v136
	v_add_f32_e32 v227, v138, v139
	v_add_f32_e32 v226, v226, v227
	v_add_f32_e32 v228, v117, v116
	v_add_f32_e32 v229, v118, v119
	v_add_f32_e32 v228, v228, v229
	v_add_f32_e32 v230, v97, v96
	v_add_f32_e32 v231, v98, v99
	v_add_f32_e32 v230, v230, v231
	v_add_f32_e32 v232, v77, v76
	v_add_f32_e32 v233, v78, v79
	v_add_f32_e32 v232, v232, v233
	v_add_f32_e32 v234, v57, v56
	v_add_f32_e32 v235, v58, v59
	v_add_f32_e32 v234, v234, v235
	ds_bpermute_b32 v221, v177, v220
	ds_bpermute_b32 v223, v177, v222
	ds_bpermute_b32 v225, v177, v224
	ds_bpermute_b32 v227, v177, v226
	ds_bpermute_b32 v229, v177, v228
	ds_bpermute_b32 v231, v177, v230
	ds_bpermute_b32 v233, v177, v232
	ds_bpermute_b32 v235, v177, v234
	s_waitcnt lgkmcnt(0)
	v_add_f32_e32 v220, v220, v221
	v_add_f32_e32 v222, v222, v223
	v_add_f32_e32 v224, v224, v225
	v_add_f32_e32 v226, v226, v227
	v_add_f32_e32 v228, v228, v229
	v_add_f32_e32 v230, v230, v231
	v_add_f32_e32 v232, v232, v233
	v_add_f32_e32 v234, v234, v235
	ds_bpermute_b32 v221, v179, v220
	ds_bpermute_b32 v223, v179, v222
	ds_bpermute_b32 v225, v179, v224
	ds_bpermute_b32 v227, v179, v226
	ds_bpermute_b32 v229, v179, v228
	ds_bpermute_b32 v231, v179, v230
	ds_bpermute_b32 v233, v179, v232
	ds_bpermute_b32 v235, v179, v234
	s_waitcnt lgkmcnt(0)
	v_add_f32_e32 v220, v220, v221
	v_add_f32_e32 v222, v222, v223
	v_add_f32_e32 v224, v224, v225
	v_add_f32_e32 v226, v226, v227
	v_add_f32_e32 v228, v228, v229
	v_add_f32_e32 v230, v230, v231
	v_add_f32_e32 v232, v232, v233
	v_add_f32_e32 v234, v234, v235
	v_fmamk_f32 v220, v220, 0x3a800000, v162
	v_fmamk_f32 v222, v222, 0x3a800000, v162
	v_fmamk_f32 v224, v224, 0x3a800000, v162
	v_fmamk_f32 v226, v226, 0x3a800000, v162
	v_fmamk_f32 v228, v228, 0x3a800000, v162
	v_fmamk_f32 v230, v230, 0x3a800000, v162
	v_fmamk_f32 v232, v232, 0x3a800000, v162
	v_fmamk_f32 v234, v234, 0x3a800000, v162
	v_rsq_f32_e32 v220, v220
	v_rsq_f32_e32 v222, v222
	v_rsq_f32_e32 v224, v224
	v_rsq_f32_e32 v226, v226
	v_rsq_f32_e32 v228, v228
	v_rsq_f32_e32 v230, v230
	v_rsq_f32_e32 v232, v232
	v_rsq_f32_e32 v234, v234
	s_nop 0
	v_mov_b32_e32 v192, v220
	v_pk_mul_f32 v[194:195], v[140:141], v[192:193] op_sel_hi:[1,0]
	v_cndmask_b32_e64 v140, 0, 1, s[0:1]
	v_pk_mul_f32 v[146:147], v[146:147], v[192:193] op_sel_hi:[1,0]
	v_pk_mul_f32 v[144:145], v[144:145], v[192:193] op_sel_hi:[1,0]
	v_pk_mul_f32 v[142:143], v[142:143], v[192:193] op_sel_hi:[1,0]
	v_cmp_ne_u32_e64 s[38:39], 1, v140
	s_andn2_b64 vcc, exec, s[0:1]
	s_cbranch_vccnz .LBB0_472
	v_max_f32_e32 v140, v144, v144
	v_max_f32_e32 v144, v195, v195
	v_max_f32_e32 v141, v194, v194
	v_max_f32_e32 v195, 0, v144
	v_max_f32_e32 v144, v146, v146
	v_max_f32_e32 v194, 0, v141
	v_max_f32_e32 v141, v145, v145
	v_max_f32_e32 v146, 0, v144
	v_max_f32_e32 v144, v147, v147
	v_max_f32_e32 v140, 0, v140
	v_max_f32_e32 v141, 0, v141
	v_max_f32_e32 v142, 0, v142
	v_max_f32_e32 v147, 0, v144
	v_max_f32_e32 v143, 0, v143
	v_pk_mul_f32 v[144:145], v[140:141], v[140:141]
	v_pk_mul_f32 v[146:147], v[146:147], v[146:147]
	v_pk_mul_f32 v[194:195], v[194:195], v[194:195]
	v_pk_mul_f32 v[142:143], v[142:143], v[142:143]
; DI unsigned pk(float lo, float hi) { return pg8::cvt_pk_bf16(lo, hi); }
;     DI void operator()(const f32x4 (&acc)[2][2][4][2], const pg8::Unit& u, int wr, int wc, int fr, int fq) const {
;     ...
;                 const int row = row0 + ai * 128 + m * 16;
;                 const f32x4 p = pp[ai * 4 + m];
;                 float s = (p[0] + p[1]) + (p[2] + p[3]);
;                 s += __shfl_xor(s, 16); s += __shfl_xor(s, 32);
;                 const float rstd = rsqrtf(s * (1.0f / D) + EPS);
;                 bf16_t* rowp = O + (size_t)row * ldc + col0;
; #pragma unroll
;                 for (int bj = 0; bj < 2; ++bj) {
;                     f32x4 v0 = acc[ai][bj][m][0] * rstd, v1 = acc[ai][bj][m][1] * rstd;
;                     if (act) {
; #pragma unroll
;                         for (int k = 0; k < 4; ++k) { float a = fmaxf(v0[k], 0.f), b = fmaxf(v1[k], 0.f); v0[k] = a * a; v1[k] = b * b; }
;                     }
;                     u32x4 w; w.x = pk(v0[0], v0[1]); w.y = pk(v0[2], v0[3]); w.z = pk(v1[0], v1[1]); w.w = pk(v1[2], v1[3]);
;                     *(u32x4*)(rowp + bj * 128) = w;
;                 }
.LBB0_472:
	v_lshl_or_b32 v140, s42, 8, v216
	v_mad_i64_i32 v[190:191], s[44:45], v190, s9, 0
	v_mov_b32_e32 v193, v192
	v_ashrrev_i32_e32 v141, 31, v140
	v_lshl_add_u64 v[190:191], v[190:191], 1, s[70:71]
	v_cvt_pk_bf16_f32 v144, v144, v145
	v_cvt_pk_bf16_f32 v145, v146, v147
	v_cvt_pk_bf16_f32 v146, v194, v195
	v_cvt_pk_bf16_f32 v147, v142, v143
	v_mov_b32_e32 v142, v192
	v_mov_b32_e32 v143, v192
	v_lshl_add_u64 v[190:191], v[140:141], 1, v[190:191]
	v_pk_mul_f32 v[134:135], v[134:135], v[142:143]
	v_pk_mul_f32 v[132:133], v[132:133], v[192:193]
	v_pk_mul_f32 v[130:131], v[130:131], v[142:143]
	s_and_b64 vcc, exec, s[38:39]
	v_pk_mul_f32 v[128:129], v[128:129], v[192:193]
	global_store_dwordx4 v[190:191], v[144:147], off nt
	s_cbranch_vccnz .LBB0_474
	v_max_f32_e32 v132, 0, v132
	v_max_f32_e32 v128, 0, v128
	v_max_f32_e32 v133, 0, v133
	v_max_f32_e32 v129, 0, v129
	v_max_f32_e32 v134, 0, v134
	v_max_f32_e32 v130, 0, v130
	v_max_f32_e32 v135, 0, v135
	v_max_f32_e32 v131, 0, v131
	v_pk_mul_f32 v[132:133], v[132:133], v[132:133]
	v_pk_mul_f32 v[134:135], v[134:135], v[134:135]
	v_pk_mul_f32 v[128:129], v[128:129], v[128:129]
	v_pk_mul_f32 v[130:131], v[130:131], v[130:131]
.LBB0_474:
	v_cvt_pk_bf16_f32 v132, v132, v133
	v_cvt_pk_bf16_f32 v133, v134, v135
	v_cvt_pk_bf16_f32 v134, v128, v129
	v_cvt_pk_bf16_f32 v135, v130, v131
	global_store_dwordx4 v[190:191], v[132:135], off offset:256 nt
	v_mov_b32_e32 v128, v222
	v_pk_mul_f32 v[126:127], v[126:127], v[128:129] op_sel_hi:[1,0]
	v_pk_mul_f32 v[124:125], v[124:125], v[128:129] op_sel_hi:[1,0]
	v_pk_mul_f32 v[122:123], v[122:123], v[128:129] op_sel_hi:[1,0]
	v_pk_mul_f32 v[120:121], v[120:121], v[128:129] op_sel_hi:[1,0]
	s_and_b64 vcc, exec, s[38:39]
	s_cbranch_vccnz .LBB0_476
	v_max_f32_e32 v124, 0, v124
	v_max_f32_e32 v120, 0, v120
	v_max_f32_e32 v125, 0, v125
	v_max_f32_e32 v121, 0, v121
	v_max_f32_e32 v126, 0, v126
	v_max_f32_e32 v122, 0, v122
	v_max_f32_e32 v127, 0, v127
	v_max_f32_e32 v123, 0, v123
	v_pk_mul_f32 v[124:125], v[124:125], v[124:125]
	v_pk_mul_f32 v[126:127], v[126:127], v[126:127]
	v_pk_mul_f32 v[120:121], v[120:121], v[120:121]
	v_pk_mul_f32 v[122:123], v[122:123], v[122:123]
.LBB0_476:
	v_mad_i64_i32 v[130:131], s[44:45], v188, s9, 0
	v_mov_b32_e32 v129, v128
	v_lshl_add_u64 v[130:131], v[130:131], 1, s[70:71]
	v_cvt_pk_bf16_f32 v124, v124, v125
	v_cvt_pk_bf16_f32 v125, v126, v127
	v_cvt_pk_bf16_f32 v126, v120, v121
	v_mov_b32_e32 v120, v128
	v_mov_b32_e32 v121, v128
	v_lshl_add_u64 v[130:131], v[140:141], 1, v[130:131]
	v_pk_mul_f32 v[114:115], v[114:115], v[120:121]
	v_pk_mul_f32 v[112:113], v[112:113], v[128:129]
	v_pk_mul_f32 v[110:111], v[110:111], v[120:121]
	s_and_b64 vcc, exec, s[38:39]
	v_pk_mul_f32 v[108:109], v[108:109], v[128:129]
	v_cvt_pk_bf16_f32 v127, v122, v123
	global_store_dwordx4 v[130:131], v[124:127], off nt
	s_cbranch_vccnz .LBB0_478
	v_max_f32_e32 v112, 0, v112
	v_max_f32_e32 v108, 0, v108
	v_max_f32_e32 v113, 0, v113
	v_max_f32_e32 v109, 0, v109
	v_max_f32_e32 v114, 0, v114
	v_max_f32_e32 v110, 0, v110
	v_max_f32_e32 v115, 0, v115
	v_max_f32_e32 v111, 0, v111
	v_pk_mul_f32 v[112:113], v[112:113], v[112:113]
	v_pk_mul_f32 v[114:115], v[114:115], v[114:115]
	v_pk_mul_f32 v[108:109], v[108:109], v[108:109]
	v_pk_mul_f32 v[110:111], v[110:111], v[110:111]
.LBB0_478:
	v_cvt_pk_bf16_f32 v112, v112, v113
	v_cvt_pk_bf16_f32 v113, v114, v115
	v_cvt_pk_bf16_f32 v114, v108, v109
	v_cvt_pk_bf16_f32 v115, v110, v111
	global_store_dwordx4 v[130:131], v[112:115], off offset:256 nt
	v_mov_b32_e32 v108, v224
	v_pk_mul_f32 v[106:107], v[106:107], v[108:109] op_sel_hi:[1,0]
	v_pk_mul_f32 v[104:105], v[104:105], v[108:109] op_sel_hi:[1,0]
	v_pk_mul_f32 v[102:103], v[102:103], v[108:109] op_sel_hi:[1,0]
	v_pk_mul_f32 v[100:101], v[100:101], v[108:109] op_sel_hi:[1,0]
	s_and_b64 vcc, exec, s[38:39]
	s_cbranch_vccnz .LBB0_480
	v_max_f32_e32 v104, 0, v104
	v_max_f32_e32 v100, 0, v100
	v_max_f32_e32 v105, 0, v105
	v_max_f32_e32 v101, 0, v101
	v_max_f32_e32 v106, 0, v106
	v_max_f32_e32 v102, 0, v102
	v_max_f32_e32 v107, 0, v107
	v_max_f32_e32 v103, 0, v103
	v_pk_mul_f32 v[104:105], v[104:105], v[104:105]
	v_pk_mul_f32 v[106:107], v[106:107], v[106:107]
	v_pk_mul_f32 v[100:101], v[100:101], v[100:101]
	v_pk_mul_f32 v[102:103], v[102:103], v[102:103]
.LBB0_480:
	v_mad_i64_i32 v[110:111], s[44:45], v186, s9, 0
	v_mov_b32_e32 v109, v108
	v_lshl_add_u64 v[110:111], v[110:111], 1, s[70:71]
	v_cvt_pk_bf16_f32 v104, v104, v105
	v_cvt_pk_bf16_f32 v105, v106, v107
	v_cvt_pk_bf16_f32 v106, v100, v101
	v_mov_b32_e32 v100, v108
	v_mov_b32_e32 v101, v108
	v_lshl_add_u64 v[110:111], v[140:141], 1, v[110:111]
	v_pk_mul_f32 v[94:95], v[94:95], v[100:101]
	v_pk_mul_f32 v[92:93], v[92:93], v[108:109]
	v_pk_mul_f32 v[90:91], v[90:91], v[100:101]
	s_and_b64 vcc, exec, s[38:39]
	v_pk_mul_f32 v[88:89], v[88:89], v[108:109]
	v_cvt_pk_bf16_f32 v107, v102, v103
	global_store_dwordx4 v[110:111], v[104:107], off nt
	s_cbranch_vccnz .LBB0_482
	v_max_f32_e32 v92, 0, v92
	v_max_f32_e32 v88, 0, v88
	v_max_f32_e32 v93, 0, v93
	v_max_f32_e32 v89, 0, v89
	v_max_f32_e32 v94, 0, v94
	v_max_f32_e32 v90, 0, v90
	v_max_f32_e32 v95, 0, v95
	v_max_f32_e32 v91, 0, v91
	v_pk_mul_f32 v[92:93], v[92:93], v[92:93]
	v_pk_mul_f32 v[94:95], v[94:95], v[94:95]
	v_pk_mul_f32 v[88:89], v[88:89], v[88:89]
	v_pk_mul_f32 v[90:91], v[90:91], v[90:91]
; DI unsigned pk(float lo, float hi) { return pg8::cvt_pk_bf16(lo, hi); }
;     DI void operator()(const f32x4 (&acc)[2][2][4][2], const pg8::Unit& u, int wr, int wc, int fr, int fq) const {
;     ...
;                 const int row = row0 + ai * 128 + m * 16;
;                 const f32x4 p = pp[ai * 4 + m];
;                 float s = (p[0] + p[1]) + (p[2] + p[3]);
;                 s += __shfl_xor(s, 16); s += __shfl_xor(s, 32);
;                 const float rstd = rsqrtf(s * (1.0f / D) + EPS);
;                 bf16_t* rowp = O + (size_t)row * ldc + col0;
; #pragma unroll
;                 for (int bj = 0; bj < 2; ++bj) {
;                     f32x4 v0 = acc[ai][bj][m][0] * rstd, v1 = acc[ai][bj][m][1] * rstd;
;                     if (act) {
; #pragma unroll
;                         for (int k = 0; k < 4; ++k) { float a = fmaxf(v0[k], 0.f), b = fmaxf(v1[k], 0.f); v0[k] = a * a; v1[k] = b * b; }
;                     }
;                     u32x4 w; w.x = pk(v0[0], v0[1]); w.y = pk(v0[2], v0[3]); w.z = pk(v1[0], v1[1]); w.w = pk(v1[2], v1[3]);
;                     *(u32x4*)(rowp + bj * 128) = w;
;                 }
.LBB0_482:
	v_cvt_pk_bf16_f32 v92, v92, v93
	v_cvt_pk_bf16_f32 v93, v94, v95
	v_cvt_pk_bf16_f32 v94, v88, v89
	v_cvt_pk_bf16_f32 v95, v90, v91
	global_store_dwordx4 v[110:111], v[92:95], off offset:256 nt
	v_mov_b32_e32 v88, v226
	v_pk_mul_f32 v[86:87], v[86:87], v[88:89] op_sel_hi:[1,0]
	v_pk_mul_f32 v[84:85], v[84:85], v[88:89] op_sel_hi:[1,0]
	v_pk_mul_f32 v[82:83], v[82:83], v[88:89] op_sel_hi:[1,0]
	v_pk_mul_f32 v[80:81], v[80:81], v[88:89] op_sel_hi:[1,0]
	s_and_b64 vcc, exec, s[38:39]
	s_cbranch_vccnz .LBB0_484
	v_max_f32_e32 v84, 0, v84
	v_max_f32_e32 v80, 0, v80
	v_max_f32_e32 v85, 0, v85
	v_max_f32_e32 v81, 0, v81
	v_max_f32_e32 v86, 0, v86
	v_max_f32_e32 v82, 0, v82
	v_max_f32_e32 v87, 0, v87
	v_max_f32_e32 v83, 0, v83
	v_pk_mul_f32 v[84:85], v[84:85], v[84:85]
	v_pk_mul_f32 v[86:87], v[86:87], v[86:87]
	v_pk_mul_f32 v[80:81], v[80:81], v[80:81]
	v_pk_mul_f32 v[82:83], v[82:83], v[82:83]
.LBB0_484:
	v_mad_i64_i32 v[90:91], s[44:45], v184, s9, 0
	v_mov_b32_e32 v89, v88
	v_lshl_add_u64 v[90:91], v[90:91], 1, s[70:71]
	v_cvt_pk_bf16_f32 v84, v84, v85
	v_cvt_pk_bf16_f32 v85, v86, v87
	v_cvt_pk_bf16_f32 v86, v80, v81
	v_mov_b32_e32 v80, v88
	v_mov_b32_e32 v81, v88
	v_lshl_add_u64 v[90:91], v[140:141], 1, v[90:91]
	v_pk_mul_f32 v[74:75], v[74:75], v[80:81]
	v_pk_mul_f32 v[72:73], v[72:73], v[88:89]
	v_pk_mul_f32 v[70:71], v[70:71], v[80:81]
	s_and_b64 vcc, exec, s[38:39]
	v_pk_mul_f32 v[68:69], v[68:69], v[88:89]
	v_cvt_pk_bf16_f32 v87, v82, v83
	global_store_dwordx4 v[90:91], v[84:87], off nt
	s_cbranch_vccnz .LBB0_486
	v_max_f32_e32 v72, 0, v72
	v_max_f32_e32 v68, 0, v68
	v_max_f32_e32 v73, 0, v73
	v_max_f32_e32 v69, 0, v69
	v_max_f32_e32 v74, 0, v74
	v_max_f32_e32 v70, 0, v70
	v_max_f32_e32 v75, 0, v75
	v_max_f32_e32 v71, 0, v71
	v_pk_mul_f32 v[72:73], v[72:73], v[72:73]
	v_pk_mul_f32 v[74:75], v[74:75], v[74:75]
	v_pk_mul_f32 v[68:69], v[68:69], v[68:69]
	v_pk_mul_f32 v[70:71], v[70:71], v[70:71]
.LBB0_486:
	v_cvt_pk_bf16_f32 v72, v72, v73
	v_cvt_pk_bf16_f32 v73, v74, v75
	v_cvt_pk_bf16_f32 v74, v68, v69
	v_cvt_pk_bf16_f32 v75, v70, v71
	global_store_dwordx4 v[90:91], v[72:75], off offset:256 nt
	v_mov_b32_e32 v68, v228
	v_pk_mul_f32 v[66:67], v[66:67], v[68:69] op_sel_hi:[1,0]
	v_pk_mul_f32 v[64:65], v[64:65], v[68:69] op_sel_hi:[1,0]
	v_pk_mul_f32 v[62:63], v[62:63], v[68:69] op_sel_hi:[1,0]
	v_pk_mul_f32 v[60:61], v[60:61], v[68:69] op_sel_hi:[1,0]
	s_and_b64 vcc, exec, s[38:39]
	s_cbranch_vccnz .LBB0_488
	v_max_f32_e32 v64, 0, v64
	v_max_f32_e32 v60, 0, v60
	v_max_f32_e32 v65, 0, v65
	v_max_f32_e32 v61, 0, v61
	v_max_f32_e32 v66, 0, v66
	v_max_f32_e32 v62, 0, v62
	v_max_f32_e32 v67, 0, v67
	v_max_f32_e32 v63, 0, v63
	v_pk_mul_f32 v[64:65], v[64:65], v[64:65]
	v_pk_mul_f32 v[66:67], v[66:67], v[66:67]
	v_pk_mul_f32 v[60:61], v[60:61], v[60:61]
	v_pk_mul_f32 v[62:63], v[62:63], v[62:63]
.LBB0_488:
	v_mad_i64_i32 v[70:71], s[44:45], v182, s9, 0
	v_mov_b32_e32 v69, v68
	v_lshl_add_u64 v[70:71], v[70:71], 1, s[70:71]
	v_cvt_pk_bf16_f32 v64, v64, v65
	v_cvt_pk_bf16_f32 v65, v66, v67
	v_cvt_pk_bf16_f32 v66, v60, v61
	v_mov_b32_e32 v60, v68
	v_mov_b32_e32 v61, v68
	v_lshl_add_u64 v[70:71], v[140:141], 1, v[70:71]
	v_pk_mul_f32 v[54:55], v[54:55], v[60:61]
	v_pk_mul_f32 v[52:53], v[52:53], v[68:69]
	v_pk_mul_f32 v[50:51], v[50:51], v[60:61]
	s_and_b64 vcc, exec, s[38:39]
	v_pk_mul_f32 v[48:49], v[48:49], v[68:69]
	v_cvt_pk_bf16_f32 v67, v62, v63
	global_store_dwordx4 v[70:71], v[64:67], off nt
	s_cbranch_vccnz .LBB0_490
	v_max_f32_e32 v52, 0, v52
	v_max_f32_e32 v48, 0, v48
	v_max_f32_e32 v53, 0, v53
	v_max_f32_e32 v49, 0, v49
	v_max_f32_e32 v54, 0, v54
	v_max_f32_e32 v50, 0, v50
	v_max_f32_e32 v55, 0, v55
	v_max_f32_e32 v51, 0, v51
	v_pk_mul_f32 v[52:53], v[52:53], v[52:53]
	v_pk_mul_f32 v[54:55], v[54:55], v[54:55]
	v_pk_mul_f32 v[48:49], v[48:49], v[48:49]
	v_pk_mul_f32 v[50:51], v[50:51], v[50:51]
.LBB0_490:
	v_cvt_pk_bf16_f32 v52, v52, v53
	v_cvt_pk_bf16_f32 v53, v54, v55
	v_cvt_pk_bf16_f32 v54, v48, v49
	v_cvt_pk_bf16_f32 v55, v50, v51
	global_store_dwordx4 v[70:71], v[52:55], off offset:256 nt
	v_mov_b32_e32 v48, v230
	v_pk_mul_f32 v[46:47], v[46:47], v[48:49] op_sel_hi:[1,0]
	v_pk_mul_f32 v[44:45], v[44:45], v[48:49] op_sel_hi:[1,0]
	v_pk_mul_f32 v[42:43], v[42:43], v[48:49] op_sel_hi:[1,0]
	v_pk_mul_f32 v[40:41], v[40:41], v[48:49] op_sel_hi:[1,0]
	s_and_b64 vcc, exec, s[38:39]
	s_cbranch_vccnz .LBB0_492
	v_max_f32_e32 v44, 0, v44
	v_max_f32_e32 v40, 0, v40
	v_max_f32_e32 v45, 0, v45
	v_max_f32_e32 v41, 0, v41
	v_max_f32_e32 v46, 0, v46
	v_max_f32_e32 v42, 0, v42
	v_max_f32_e32 v47, 0, v47
	v_max_f32_e32 v43, 0, v43
	v_pk_mul_f32 v[44:45], v[44:45], v[44:45]
	v_pk_mul_f32 v[46:47], v[46:47], v[46:47]
	v_pk_mul_f32 v[40:41], v[40:41], v[40:41]
	v_pk_mul_f32 v[42:43], v[42:43], v[42:43]
; DI unsigned pk(float lo, float hi) { return pg8::cvt_pk_bf16(lo, hi); }
;     DI void operator()(const f32x4 (&acc)[2][2][4][2], const pg8::Unit& u, int wr, int wc, int fr, int fq) const {
;     ...
;                 const int row = row0 + ai * 128 + m * 16;
;                 const f32x4 p = pp[ai * 4 + m];
;                 float s = (p[0] + p[1]) + (p[2] + p[3]);
;                 s += __shfl_xor(s, 16); s += __shfl_xor(s, 32);
;                 const float rstd = rsqrtf(s * (1.0f / D) + EPS);
;                 bf16_t* rowp = O + (size_t)row * ldc + col0;
; #pragma unroll
;                 for (int bj = 0; bj < 2; ++bj) {
;                     f32x4 v0 = acc[ai][bj][m][0] * rstd, v1 = acc[ai][bj][m][1] * rstd;
;                     if (act) {
; #pragma unroll
;                         for (int k = 0; k < 4; ++k) { float a = fmaxf(v0[k], 0.f), b = fmaxf(v1[k], 0.f); v0[k] = a * a; v1[k] = b * b; }
;                     }
;                     u32x4 w; w.x = pk(v0[0], v0[1]); w.y = pk(v0[2], v0[3]); w.z = pk(v1[0], v1[1]); w.w = pk(v1[2], v1[3]);
;                     *(u32x4*)(rowp + bj * 128) = w;
;                 }
.LBB0_492:
	v_mad_i64_i32 v[50:51], s[44:45], v180, s9, 0
	v_mov_b32_e32 v49, v48
	v_lshl_add_u64 v[50:51], v[50:51], 1, s[70:71]
	v_cvt_pk_bf16_f32 v44, v44, v45
	v_cvt_pk_bf16_f32 v45, v46, v47
	v_cvt_pk_bf16_f32 v46, v40, v41
	v_mov_b32_e32 v40, v48
	v_mov_b32_e32 v41, v48
	v_lshl_add_u64 v[50:51], v[140:141], 1, v[50:51]
	v_pk_mul_f32 v[38:39], v[38:39], v[40:41]
	v_pk_mul_f32 v[36:37], v[36:37], v[48:49]
	v_pk_mul_f32 v[34:35], v[34:35], v[40:41]
	s_and_b64 vcc, exec, s[38:39]
	v_pk_mul_f32 v[32:33], v[32:33], v[48:49]
	v_cvt_pk_bf16_f32 v47, v42, v43
	global_store_dwordx4 v[50:51], v[44:47], off nt
	s_cbranch_vccnz .LBB0_494
	v_max_f32_e32 v36, 0, v36
	v_max_f32_e32 v32, 0, v32
	v_max_f32_e32 v37, 0, v37
	v_max_f32_e32 v33, 0, v33
	v_max_f32_e32 v38, 0, v38
	v_max_f32_e32 v34, 0, v34
	v_max_f32_e32 v39, 0, v39
	v_max_f32_e32 v35, 0, v35
	v_pk_mul_f32 v[36:37], v[36:37], v[36:37]
	v_pk_mul_f32 v[38:39], v[38:39], v[38:39]
	v_pk_mul_f32 v[32:33], v[32:33], v[32:33]
	v_pk_mul_f32 v[34:35], v[34:35], v[34:35]
.LBB0_494:
	v_cvt_pk_bf16_f32 v36, v36, v37
	v_cvt_pk_bf16_f32 v37, v38, v39
	v_cvt_pk_bf16_f32 v38, v32, v33
	v_cvt_pk_bf16_f32 v39, v34, v35
	global_store_dwordx4 v[50:51], v[36:39], off offset:256 nt
	v_mov_b32_e32 v32, v232
	v_pk_mul_f32 v[30:31], v[30:31], v[32:33] op_sel_hi:[1,0]
	v_pk_mul_f32 v[28:29], v[28:29], v[32:33] op_sel_hi:[1,0]
	v_pk_mul_f32 v[26:27], v[26:27], v[32:33] op_sel_hi:[1,0]
	v_pk_mul_f32 v[24:25], v[24:25], v[32:33] op_sel_hi:[1,0]
	s_and_b64 vcc, exec, s[38:39]
	s_cbranch_vccnz .LBB0_496
	v_max_f32_e32 v28, 0, v28
	v_max_f32_e32 v24, 0, v24
	v_max_f32_e32 v29, 0, v29
	v_max_f32_e32 v25, 0, v25
	v_max_f32_e32 v30, 0, v30
	v_max_f32_e32 v26, 0, v26
	v_max_f32_e32 v31, 0, v31
	v_max_f32_e32 v27, 0, v27
	v_pk_mul_f32 v[28:29], v[28:29], v[28:29]
	v_pk_mul_f32 v[30:31], v[30:31], v[30:31]
	v_pk_mul_f32 v[24:25], v[24:25], v[24:25]
	v_pk_mul_f32 v[26:27], v[26:27], v[26:27]
.LBB0_496:
	v_mad_i64_i32 v[34:35], s[44:45], v178, s9, 0
	v_mov_b32_e32 v33, v32
	v_lshl_add_u64 v[34:35], v[34:35], 1, s[70:71]
	v_cvt_pk_bf16_f32 v28, v28, v29
	v_cvt_pk_bf16_f32 v29, v30, v31
	v_cvt_pk_bf16_f32 v30, v24, v25
	v_mov_b32_e32 v24, v32
	v_mov_b32_e32 v25, v32
	v_lshl_add_u64 v[34:35], v[140:141], 1, v[34:35]
	v_pk_mul_f32 v[22:23], v[22:23], v[24:25]
	v_pk_mul_f32 v[20:21], v[20:21], v[32:33]
	v_pk_mul_f32 v[18:19], v[18:19], v[24:25]
	s_and_b64 vcc, exec, s[38:39]
	v_pk_mul_f32 v[16:17], v[16:17], v[32:33]
	v_cvt_pk_bf16_f32 v31, v26, v27
	global_store_dwordx4 v[34:35], v[28:31], off nt
	s_cbranch_vccnz .LBB0_498
	v_max_f32_e32 v20, 0, v20
	v_max_f32_e32 v16, 0, v16
	v_max_f32_e32 v21, 0, v21
	v_max_f32_e32 v17, 0, v17
	v_max_f32_e32 v22, 0, v22
	v_max_f32_e32 v18, 0, v18
	v_max_f32_e32 v23, 0, v23
	v_max_f32_e32 v19, 0, v19
	v_pk_mul_f32 v[20:21], v[20:21], v[20:21]
	v_pk_mul_f32 v[22:23], v[22:23], v[22:23]
	v_pk_mul_f32 v[16:17], v[16:17], v[16:17]
	v_pk_mul_f32 v[18:19], v[18:19], v[18:19]
.LBB0_498:
	v_cvt_pk_bf16_f32 v20, v20, v21
	v_cvt_pk_bf16_f32 v21, v22, v23
	v_cvt_pk_bf16_f32 v22, v16, v17
	v_cvt_pk_bf16_f32 v23, v18, v19
	global_store_dwordx4 v[34:35], v[20:23], off offset:256 nt
	v_mov_b32_e32 v16, v234
	v_pk_mul_f32 v[14:15], v[14:15], v[16:17] op_sel_hi:[1,0]
	v_pk_mul_f32 v[12:13], v[12:13], v[16:17] op_sel_hi:[1,0]
	v_pk_mul_f32 v[10:11], v[10:11], v[16:17] op_sel_hi:[1,0]
	v_pk_mul_f32 v[8:9], v[8:9], v[16:17] op_sel_hi:[1,0]
	s_and_b64 vcc, exec, s[38:39]
	s_cbranch_vccnz .LBB0_500
	v_max_f32_e32 v12, 0, v12
	v_max_f32_e32 v8, 0, v8
	v_max_f32_e32 v13, 0, v13
	v_max_f32_e32 v9, 0, v9
	v_max_f32_e32 v14, 0, v14
	v_max_f32_e32 v10, 0, v10
	v_max_f32_e32 v15, 0, v15
	v_max_f32_e32 v11, 0, v11
	v_pk_mul_f32 v[12:13], v[12:13], v[12:13]
	v_pk_mul_f32 v[14:15], v[14:15], v[14:15]
	v_pk_mul_f32 v[8:9], v[8:9], v[8:9]
	v_pk_mul_f32 v[10:11], v[10:11], v[10:11]
.LBB0_500:
	v_mad_i64_i32 v[18:19], s[44:45], v176, s9, 0
	v_mov_b32_e32 v17, v16
	v_lshl_add_u64 v[18:19], v[18:19], 1, s[70:71]
	v_cvt_pk_bf16_f32 v12, v12, v13
	v_cvt_pk_bf16_f32 v13, v14, v15
	v_cvt_pk_bf16_f32 v14, v8, v9
	v_mov_b32_e32 v8, v16
	v_mov_b32_e32 v9, v16
	v_lshl_add_u64 v[18:19], v[140:141], 1, v[18:19]
	v_pk_mul_f32 v[6:7], v[6:7], v[8:9]
	v_pk_mul_f32 v[4:5], v[4:5], v[16:17]
	v_pk_mul_f32 v[2:3], v[2:3], v[8:9]
	s_and_b64 vcc, exec, s[38:39]
	v_pk_mul_f32 v[0:1], v[0:1], v[16:17]
	v_cvt_pk_bf16_f32 v15, v10, v11
	global_store_dwordx4 v[18:19], v[12:15], off nt
	s_cbranch_vccnz .LBB0_502
	v_max_f32_e32 v4, 0, v4
	v_max_f32_e32 v0, 0, v0
	v_max_f32_e32 v5, 0, v5
	v_max_f32_e32 v1, 0, v1
	v_max_f32_e32 v6, 0, v6
	v_max_f32_e32 v2, 0, v2
	v_max_f32_e32 v7, 0, v7
	v_max_f32_e32 v3, 0, v3
	v_pk_mul_f32 v[4:5], v[4:5], v[4:5]
	v_pk_mul_f32 v[6:7], v[6:7], v[6:7]
	v_pk_mul_f32 v[0:1], v[0:1], v[0:1]
	v_pk_mul_f32 v[2:3], v[2:3], v[2:3]
